# MLA-up: MMA fragment reads through an 8-slot register ring with counted lgkmcnt (was lgkmcnt(0) per MFMA); rope cos/sin loaded once per item
# baseline (speedup 1.0000x reference)
; DI int crow(int r, int hh) { return (r & 3) + 8 * (r >> 2) + 4 * hh; }
; DI void phase_mla_up(const Params& p, int layer, char* lds) {
;     ...
;       auto wload = [&](int ct) {
;         int tl = tid; asm volatile("" : "+v"(tl));
; #pragma unroll
;         for (int i = 0; i < 6; ++i) { const int c = tl + NTHR * i; if (c < 128 * CPR) rw[i] = *(const u32x4*)(Wt + (size_t)ct * 128 * K + c * 8); }
;       };
;     ...
;       float rv[16];
; #pragma unroll
;       for (int r = 0; r < 16; ++r) rv[r] = rinv[32 * wm + crow(r, hh)] * (part == 0 ? QSC : 1.f);
;       const int rowb = m0 + 32 * wm + 4 * hh;
;       const int bq = m0 >> 13, srow = rowb & (S - 1);
;       auto epi = [&](const f32x16& acc, const int c0) {
;         if (part == 0) {
;           const bool is_rope = (c0 % 96 == 64);
;           u16* qp = QB + (size_t)rowb * QW + c0 + l32;
;           const f32x2* rp = rt + (size_t)srow * 16 + (l32 & 15);
.LBB0_176:
	s_or_b64 exec, exec, s[24:25]
	s_waitcnt lgkmcnt(0)
	s_barrier
	ds_read_b128 v[18:21], v92
	ds_read_b128 v[14:17], v92 offset:32
	ds_read_b128 v[10:13], v92 offset:64
	ds_read_b128 v[6:9], v92 offset:96
	s_and_b64 vcc, s[12:13], exec
	s_cbranch_vccz .Lrope_pre_skip
	global_load_dwordx2 v[116:117], v[76:77], off
	global_load_dwordx2 v[118:119], v[76:77], off offset:128
	global_load_dwordx2 v[120:121], v[76:77], off offset:256
	global_load_dwordx2 v[122:123], v[76:77], off offset:384
	global_load_dwordx2 v[124:125], v[76:77], off offset:1024
	global_load_dwordx2 v[126:127], v[76:77], off offset:1152
	global_load_dwordx2 v[128:129], v[76:77], off offset:1280
	global_load_dwordx2 v[130:131], v[76:77], off offset:1408
	global_load_dwordx2 v[132:133], v[76:77], off offset:2048
	global_load_dwordx2 v[134:135], v[76:77], off offset:2176
	global_load_dwordx2 v[136:137], v[76:77], off offset:2304
	global_load_dwordx2 v[138:139], v[76:77], off offset:2432
	global_load_dwordx2 v[140:141], v[76:77], off offset:3072
	global_load_dwordx2 v[142:143], v[76:77], off offset:3200
	global_load_dwordx2 v[144:145], v[76:77], off offset:3328
	global_load_dwordx2 v[146:147], v[76:77], off offset:3456
.Lrope_pre_skip:
	s_and_b64 s[24:25], s[12:13], exec
	v_mov_b32_e32 v4, v59
	s_cselect_b32 s25, s44, s60
	s_cselect_b32 s24, s23, s52
	s_nop 0
	v_cmp_gt_i32_e32 vcc, s93, v4
	s_and_saveexec_b64 s[26:27], vcc
	s_cbranch_execz .LBB0_178
	s_waitcnt vmcnt(0)
	v_lshlrev_b32_e32 v0, 3, v4
	v_ashrrev_i32_e32 v1, 31, v0
	v_lshl_add_u64 v[0:1], v[0:1], 1, s[24:25]
	global_load_dwordx4 v[0:3], v[0:1], off

; DI void phase_mla_up(const Params& p, int layer, char* lds) {
;     ...
;         if (part == 0) P2_MMA(12, 400); else P2_MMA(8, 272);
.LBB0_217:
	s_andn2_b64 vcc, exec, s[20:21]
	s_mov_b64 s[12:13], -1
	s_cbranch_vccnz .LBB0_220
	v_add_u32_e32 v4, v88, v85
	v_add_u32_e32 v79, v90, v85
	ds_read_b128 v[112:115], v4
	ds_read_b128 v[186:189], v79 offset:51200
	ds_read_b128 v[204:207], v79 offset:59904
	ds_read_b128 v[222:225], v4 offset:32
	ds_read_b128 v[226:229], v79 offset:51232
	ds_read_b128 v[230:233], v79 offset:59936
	ds_read_b128 v[234:237], v4 offset:64
	ds_read_b128 v[248:251], v79 offset:51264
	s_waitcnt lgkmcnt(6)
	v_mfma_f32_32x32x16_bf16 v[22:37], v[112:115], v[186:189], 0
	ds_read_b128 v[186:189], v79 offset:59968
	s_waitcnt lgkmcnt(6)
	v_mfma_f32_32x32x16_bf16 v[6:21], v[112:115], v[204:207], 0
	ds_read_b128 v[204:207], v4 offset:96
	ds_read_b128 v[112:115], v79 offset:51296
	s_waitcnt lgkmcnt(6)
	v_mfma_f32_32x32x16_bf16 v[22:37], v[222:225], v[226:229], v[22:37]
	ds_read_b128 v[226:229], v79 offset:60000
	s_waitcnt lgkmcnt(6)
	v_mfma_f32_32x32x16_bf16 v[6:21], v[222:225], v[230:233], v[6:21]
	ds_read_b128 v[230:233], v4 offset:128
	ds_read_b128 v[222:225], v79 offset:51328
	s_waitcnt lgkmcnt(6)
	v_mfma_f32_32x32x16_bf16 v[22:37], v[234:237], v[248:251], v[22:37]
	ds_read_b128 v[248:251], v79 offset:60032
	s_waitcnt lgkmcnt(6)
	v_mfma_f32_32x32x16_bf16 v[6:21], v[234:237], v[186:189], v[6:21]
	ds_read_b128 v[186:189], v4 offset:160
	ds_read_b128 v[234:237], v79 offset:51360
	s_waitcnt lgkmcnt(6)
	v_mfma_f32_32x32x16_bf16 v[22:37], v[204:207], v[112:115], v[22:37]
	ds_read_b128 v[112:115], v79 offset:60064
	s_waitcnt lgkmcnt(6)
	v_mfma_f32_32x32x16_bf16 v[6:21], v[204:207], v[226:229], v[6:21]
	ds_read_b128 v[226:229], v4 offset:192
	ds_read_b128 v[204:207], v79 offset:51392
	s_waitcnt lgkmcnt(6)
	v_mfma_f32_32x32x16_bf16 v[22:37], v[230:233], v[222:225], v[22:37]
	ds_read_b128 v[222:225], v79 offset:60096
	s_waitcnt lgkmcnt(6)
	v_mfma_f32_32x32x16_bf16 v[6:21], v[230:233], v[248:251], v[6:21]
	ds_read_b128 v[248:251], v4 offset:224
	ds_read_b128 v[230:233], v79 offset:51424
	s_waitcnt lgkmcnt(6)
	v_mfma_f32_32x32x16_bf16 v[22:37], v[186:189], v[234:237], v[22:37]
	ds_read_b128 v[234:237], v79 offset:60128
	s_waitcnt lgkmcnt(6)
	v_mfma_f32_32x32x16_bf16 v[6:21], v[186:189], v[112:115], v[6:21]
	s_waitcnt lgkmcnt(4)
	v_mfma_f32_32x32x16_bf16 v[22:37], v[226:229], v[204:207], v[22:37]
	s_waitcnt lgkmcnt(3)
	v_mfma_f32_32x32x16_bf16 v[6:21], v[226:229], v[222:225], v[6:21]
	s_waitcnt lgkmcnt(1)
	v_mfma_f32_32x32x16_bf16 v[22:37], v[248:251], v[230:233], v[22:37]
	s_waitcnt lgkmcnt(0)
	v_mfma_f32_32x32x16_bf16 v[6:21], v[248:251], v[234:237], v[6:21]
	s_cbranch_execz .LBB0_221

; DI void phase_mla_up(const Params& p, int layer, char* lds) {
;     ...
;         if (part == 0) P2_MMA(12, 400); else P2_MMA(8, 272);
;     ...
;         const int c0 = ct * 128 + 64 * wn;
;         if (c0 < NOUT) epi(acc0, c0);
.LBB0_221:
	s_nop 10
	ds_read_b128 v[112:115], v93
	ds_read_b128 v[186:189], v94 offset:51200
	ds_read_b128 v[204:207], v94 offset:64000
	ds_read_b128 v[222:225], v93 offset:32
	ds_read_b128 v[226:229], v94 offset:51232
	ds_read_b128 v[230:233], v94 offset:64032
	ds_read_b128 v[234:237], v93 offset:64
	ds_read_b128 v[248:251], v94 offset:51264
	s_waitcnt lgkmcnt(6)
	v_mfma_f32_32x32x16_bf16 v[22:37], v[112:115], v[186:189], 0
	ds_read_b128 v[186:189], v94 offset:64064
	s_waitcnt lgkmcnt(6)
	v_mfma_f32_32x32x16_bf16 v[6:21], v[112:115], v[204:207], 0
	ds_read_b128 v[204:207], v93 offset:96
	ds_read_b128 v[112:115], v94 offset:51296
	s_waitcnt lgkmcnt(6)
	v_mfma_f32_32x32x16_bf16 v[22:37], v[222:225], v[226:229], v[22:37]
	ds_read_b128 v[226:229], v94 offset:64096
	s_waitcnt lgkmcnt(6)
	v_mfma_f32_32x32x16_bf16 v[6:21], v[222:225], v[230:233], v[6:21]
	ds_read_b128 v[230:233], v93 offset:128
	ds_read_b128 v[222:225], v94 offset:51328
	s_waitcnt lgkmcnt(6)
	v_mfma_f32_32x32x16_bf16 v[22:37], v[234:237], v[248:251], v[22:37]
	ds_read_b128 v[248:251], v94 offset:64128
	s_waitcnt lgkmcnt(6)
	v_mfma_f32_32x32x16_bf16 v[6:21], v[234:237], v[186:189], v[6:21]
	ds_read_b128 v[186:189], v93 offset:160
	ds_read_b128 v[234:237], v94 offset:51360
	s_waitcnt lgkmcnt(6)
	v_mfma_f32_32x32x16_bf16 v[22:37], v[204:207], v[112:115], v[22:37]
	ds_read_b128 v[112:115], v94 offset:64160
	s_waitcnt lgkmcnt(6)
	v_mfma_f32_32x32x16_bf16 v[6:21], v[204:207], v[226:229], v[6:21]
	ds_read_b128 v[226:229], v93 offset:192
	ds_read_b128 v[204:207], v94 offset:51392
	s_waitcnt lgkmcnt(6)
	v_mfma_f32_32x32x16_bf16 v[22:37], v[230:233], v[222:225], v[22:37]
	ds_read_b128 v[222:225], v94 offset:64192
	s_waitcnt lgkmcnt(6)
	v_mfma_f32_32x32x16_bf16 v[6:21], v[230:233], v[248:251], v[6:21]
	ds_read_b128 v[248:251], v93 offset:224
	ds_read_b128 v[230:233], v94 offset:51424
	s_waitcnt lgkmcnt(6)
	v_mfma_f32_32x32x16_bf16 v[22:37], v[186:189], v[234:237], v[22:37]
	ds_read_b128 v[234:237], v94 offset:64224
	s_waitcnt lgkmcnt(6)
	v_mfma_f32_32x32x16_bf16 v[6:21], v[186:189], v[112:115], v[6:21]
	ds_read_b128 v[112:115], v93 offset:256
	ds_read_b128 v[186:189], v94 offset:51456
	s_waitcnt lgkmcnt(6)
	v_mfma_f32_32x32x16_bf16 v[22:37], v[226:229], v[204:207], v[22:37]
	ds_read_b128 v[204:207], v94 offset:64256
	s_waitcnt lgkmcnt(6)
	v_mfma_f32_32x32x16_bf16 v[6:21], v[226:229], v[222:225], v[6:21]
	ds_read_b128 v[222:225], v93 offset:288
	ds_read_b128 v[226:229], v94 offset:51488
	s_waitcnt lgkmcnt(6)
	v_mfma_f32_32x32x16_bf16 v[22:37], v[248:251], v[230:233], v[22:37]
	ds_read_b128 v[230:233], v94 offset:64288
	s_waitcnt lgkmcnt(6)
	v_mfma_f32_32x32x16_bf16 v[6:21], v[248:251], v[234:237], v[6:21]
	ds_read_b128 v[234:237], v93 offset:320
	ds_read_b128 v[248:251], v94 offset:51520
	s_waitcnt lgkmcnt(6)
	v_mfma_f32_32x32x16_bf16 v[22:37], v[112:115], v[186:189], v[22:37]
	ds_read_b128 v[186:189], v94 offset:64320
	s_waitcnt lgkmcnt(6)
	v_mfma_f32_32x32x16_bf16 v[6:21], v[112:115], v[204:207], v[6:21]
	ds_read_b128 v[204:207], v93 offset:352
	ds_read_b128 v[112:115], v94 offset:51552
	s_waitcnt lgkmcnt(6)
	v_mfma_f32_32x32x16_bf16 v[22:37], v[222:225], v[226:229], v[22:37]
	ds_read_b128 v[226:229], v94 offset:64352
	s_waitcnt lgkmcnt(6)
	v_mfma_f32_32x32x16_bf16 v[6:21], v[222:225], v[230:233], v[6:21]
	s_waitcnt lgkmcnt(4)
	v_mfma_f32_32x32x16_bf16 v[22:37], v[234:237], v[248:251], v[22:37]
	s_waitcnt lgkmcnt(3)
	v_mfma_f32_32x32x16_bf16 v[6:21], v[234:237], v[186:189], v[6:21]
	s_waitcnt lgkmcnt(1)
	v_mfma_f32_32x32x16_bf16 v[22:37], v[204:207], v[112:115], v[22:37]
	s_waitcnt lgkmcnt(0)
	v_mfma_f32_32x32x16_bf16 v[6:21], v[204:207], v[226:229], v[6:21]
	v_cmp_gt_i32_e32 vcc, s73, v78
	s_and_saveexec_b64 s[26:27], vcc
	s_cbranch_execz .LBB0_262

; DI unsigned pk2(float lo, float hi) { f32x2 v = {lo, hi}; b16x2 r = __builtin_convertvector(v, b16x2); return __builtin_bit_cast(unsigned, r); }
; DI void phase_mla_up(const Params& p, int layer, char* lds) {
;     ...
;       auto epi = [&](const f32x16& acc, const int c0) {
;         if (part == 0) {
;           const bool is_rope = (c0 % 96 == 64);
;           u16* qp = QB + (size_t)rowb * QW + c0 + l32;
;           const f32x2* rp = rt + (size_t)srow * 16 + (l32 & 15);
; #pragma unroll
;           for (int r = 0; r < 16; ++r) {
;             const int ro = (r & 3) + 8 * (r >> 2);
;             float v = acc[r] * rv[r];
;             if (is_rope) {
;               float o = __shfl_xor(v, 16);
;               f32x2 cs = rp[ro * 16];
;               v = (l32 < 16) ? (v * cs[0] - o * cs[1]) : (v * cs[0] + o * cs[1]);
;             }
;             qp[ro * QW] = (u16)(pk2(v, 0.f) & 0xffffu);
;           }
.LBB0_228:
	s_andn2_b64 vcc, exec, s[12:13]
	s_cbranch_vccnz .LBB0_262
	v_mul_hi_i32 v4, v78, s95
	v_lshrrev_b32_e32 v79, 31, v4
	v_lshrrev_b32_e32 v4, 4, v4
	v_add_u32_e32 v4, v4, v79
	v_mul_lo_u32 v4, v4, s61
	v_sub_u32_e32 v4, v78, v4
	v_cmp_eq_u32_e64 s[12:13], 64, v4
	v_mul_f32_e32 v4, v95, v22
	s_and_saveexec_b64 s[54:55], s[12:13]
	s_cbranch_execz .LBB0_231
	v_mov_b32_e32 v238, v4
	v_mov_b32_e32 v239, v4
	s_nop 1
	v_permlane16_swap_b32_e32 v238, v239
	v_cndmask_b32_e64 v238, v238, v239, s[8:9]
	v_mul_f32_e32 v238, v117, v238
	v_cndmask_b32_e64 v238, v238, -v238, s[8:9]
	v_fmac_f32_e32 v238, v4, v116
	v_mov_b32_e32 v4, v238
.LBB0_231:
	s_or_b64 exec, exec, s[54:55]
	v_ashrrev_i32_e32 v79, 31, v78
	v_lshl_add_u64 v[80:81], v[78:79], 1, v[74:75]
	v_cvt_pk_bf16_f32 v4, v4, s0
	global_store_short v[80:81], v4, off
	v_mul_f32_e32 v4, v96, v23
	s_and_saveexec_b64 s[54:55], s[12:13]
	s_cbranch_execz .LBB0_233
	v_mov_b32_e32 v238, v4
	v_mov_b32_e32 v239, v4
	s_nop 1
	v_permlane16_swap_b32_e32 v238, v239
	v_cndmask_b32_e64 v238, v238, v239, s[8:9]
	v_mul_f32_e32 v238, v119, v238
	v_cndmask_b32_e64 v238, v238, -v238, s[8:9]
	v_fmac_f32_e32 v238, v4, v118
	v_mov_b32_e32 v4, v238
.LBB0_233:
	s_or_b64 exec, exec, s[54:55]
	v_cvt_pk_bf16_f32 v4, v4, s0
	global_store_short v[80:81], v4, off offset:1152
	v_mul_f32_e32 v4, v97, v24
	s_and_saveexec_b64 s[54:55], s[12:13]
	s_cbranch_execz .LBB0_235
	v_mov_b32_e32 v238, v4
	v_mov_b32_e32 v239, v4
	s_nop 1
	v_permlane16_swap_b32_e32 v238, v239
	v_cndmask_b32_e64 v238, v238, v239, s[8:9]
	v_mul_f32_e32 v238, v121, v238
	v_cndmask_b32_e64 v238, v238, -v238, s[8:9]
	v_fmac_f32_e32 v238, v4, v120
	v_mov_b32_e32 v4, v238
.LBB0_235:
	s_or_b64 exec, exec, s[54:55]
	v_cvt_pk_bf16_f32 v4, v4, s0
	global_store_short v[80:81], v4, off offset:2304
	v_mul_f32_e32 v4, v98, v25
	s_and_saveexec_b64 s[54:55], s[12:13]
	s_cbranch_execz .LBB0_237
	v_mov_b32_e32 v238, v4
	v_mov_b32_e32 v239, v4
	s_nop 1
	v_permlane16_swap_b32_e32 v238, v239
	v_cndmask_b32_e64 v238, v238, v239, s[8:9]
	v_mul_f32_e32 v238, v123, v238
	v_cndmask_b32_e64 v238, v238, -v238, s[8:9]
	v_fmac_f32_e32 v238, v4, v122
	v_mov_b32_e32 v4, v238
.LBB0_237:
	s_or_b64 exec, exec, s[54:55]
	v_cvt_pk_bf16_f32 v4, v4, s0
	global_store_short v[80:81], v4, off offset:3456
	v_mul_f32_e32 v4, v99, v26
	s_and_saveexec_b64 s[54:55], s[12:13]
	s_cbranch_execz .LBB0_239
	v_mov_b32_e32 v238, v4
	v_mov_b32_e32 v239, v4
	s_nop 1
	v_permlane16_swap_b32_e32 v238, v239
	v_cndmask_b32_e64 v238, v238, v239, s[8:9]
	v_mul_f32_e32 v238, v125, v238
	v_cndmask_b32_e64 v238, v238, -v238, s[8:9]
	v_fmac_f32_e32 v238, v4, v124
	v_mov_b32_e32 v4, v238
.LBB0_239:
	s_or_b64 exec, exec, s[54:55]
	v_add_co_u32_e32 v22, vcc, 0x2000, v80
	v_cvt_pk_bf16_f32 v4, v4, s0
	s_nop 0
	v_addc_co_u32_e32 v23, vcc, 0, v81, vcc
	global_store_short v[22:23], v4, off offset:1024
	v_mul_f32_e32 v4, v100, v27
	s_and_saveexec_b64 s[54:55], s[12:13]
	s_cbranch_execz .LBB0_241
	v_mov_b32_e32 v238, v4
	v_mov_b32_e32 v239, v4
	s_nop 1
	v_permlane16_swap_b32_e32 v238, v239
	v_cndmask_b32_e64 v238, v238, v239, s[8:9]
	v_mul_f32_e32 v238, v127, v238
	v_cndmask_b32_e64 v238, v238, -v238, s[8:9]
	v_fmac_f32_e32 v238, v4, v126
	v_mov_b32_e32 v4, v238
.LBB0_241:
	s_or_b64 exec, exec, s[54:55]
	v_add_co_u32_e32 v22, vcc, 0x2000, v80
	v_cvt_pk_bf16_f32 v4, v4, s0
	s_nop 0
	v_addc_co_u32_e32 v23, vcc, 0, v81, vcc
	global_store_short v[22:23], v4, off offset:2176
	v_mul_f32_e32 v4, v101, v28
	s_and_saveexec_b64 s[54:55], s[12:13]
	s_cbranch_execz .LBB0_243
	v_mov_b32_e32 v238, v4
	v_mov_b32_e32 v239, v4
	s_nop 1
	v_permlane16_swap_b32_e32 v238, v239
	v_cndmask_b32_e64 v238, v238, v239, s[8:9]
	v_mul_f32_e32 v238, v129, v238
	v_cndmask_b32_e64 v238, v238, -v238, s[8:9]
	v_fmac_f32_e32 v238, v4, v128
	v_mov_b32_e32 v4, v238
.LBB0_243:
	s_or_b64 exec, exec, s[54:55]
	v_add_co_u32_e32 v22, vcc, 0x2000, v80
	v_cvt_pk_bf16_f32 v4, v4, s0
	s_nop 0
	v_addc_co_u32_e32 v23, vcc, 0, v81, vcc
	global_store_short v[22:23], v4, off offset:3328
	v_mul_f32_e32 v4, v102, v29
	s_and_saveexec_b64 s[54:55], s[12:13]
	s_cbranch_execz .LBB0_245
	v_mov_b32_e32 v238, v4
	v_mov_b32_e32 v239, v4
	s_nop 1
	v_permlane16_swap_b32_e32 v238, v239
	v_cndmask_b32_e64 v238, v238, v239, s[8:9]
	v_mul_f32_e32 v238, v131, v238
	v_cndmask_b32_e64 v238, v238, -v238, s[8:9]
	v_fmac_f32_e32 v238, v4, v130
	v_mov_b32_e32 v4, v238
; DI unsigned pk2(float lo, float hi) { f32x2 v = {lo, hi}; b16x2 r = __builtin_convertvector(v, b16x2); return __builtin_bit_cast(unsigned, r); }
; DI void phase_mla_up(const Params& p, int layer, char* lds) {
;     ...
;           for (int r = 0; r < 16; ++r) {
;             const int ro = (r & 3) + 8 * (r >> 2);
;             float v = acc[r] * rv[r];
;             if (is_rope) {
;               float o = __shfl_xor(v, 16);
;               f32x2 cs = rp[ro * 16];
;               v = (l32 < 16) ? (v * cs[0] - o * cs[1]) : (v * cs[0] + o * cs[1]);
;             }
;             qp[ro * QW] = (u16)(pk2(v, 0.f) & 0xffffu);
;           }
.LBB0_245:
	s_or_b64 exec, exec, s[54:55]
	v_add_co_u32_e32 v22, vcc, 0x3000, v80
	v_cvt_pk_bf16_f32 v4, v4, s0
	s_nop 0
	v_addc_co_u32_e32 v23, vcc, 0, v81, vcc
	global_store_short v[22:23], v4, off offset:384
	v_mul_f32_e32 v4, v103, v30
	s_and_saveexec_b64 s[54:55], s[12:13]
	s_cbranch_execz .LBB0_247
	v_mov_b32_e32 v238, v4
	v_mov_b32_e32 v239, v4
	s_nop 1
	v_permlane16_swap_b32_e32 v238, v239
	v_cndmask_b32_e64 v238, v238, v239, s[8:9]
	v_mul_f32_e32 v238, v133, v238
	v_cndmask_b32_e64 v238, v238, -v238, s[8:9]
	v_fmac_f32_e32 v238, v4, v132
	v_mov_b32_e32 v4, v238
.LBB0_247:
	s_or_b64 exec, exec, s[54:55]
	v_add_co_u32_e32 v22, vcc, 0x4000, v80
	v_cvt_pk_bf16_f32 v4, v4, s0
	s_nop 0
	v_addc_co_u32_e32 v23, vcc, 0, v81, vcc
	global_store_short v[22:23], v4, off offset:2048
	v_mul_f32_e32 v4, v104, v31
	s_and_saveexec_b64 s[54:55], s[12:13]
	s_cbranch_execz .LBB0_249
	v_mov_b32_e32 v238, v4
	v_mov_b32_e32 v239, v4
	s_nop 1
	v_permlane16_swap_b32_e32 v238, v239
	v_cndmask_b32_e64 v238, v238, v239, s[8:9]
	v_mul_f32_e32 v238, v135, v238
	v_cndmask_b32_e64 v238, v238, -v238, s[8:9]
	v_fmac_f32_e32 v238, v4, v134
	v_mov_b32_e32 v4, v238
.LBB0_249:
	s_or_b64 exec, exec, s[54:55]
	v_add_co_u32_e32 v22, vcc, 0x4000, v80
	v_cvt_pk_bf16_f32 v4, v4, s0
	s_nop 0
	v_addc_co_u32_e32 v23, vcc, 0, v81, vcc
	global_store_short v[22:23], v4, off offset:3200
	v_mul_f32_e32 v4, v105, v32
	s_and_saveexec_b64 s[54:55], s[12:13]
	s_cbranch_execz .LBB0_251
	v_mov_b32_e32 v238, v4
	v_mov_b32_e32 v239, v4
	s_nop 1
	v_permlane16_swap_b32_e32 v238, v239
	v_cndmask_b32_e64 v238, v238, v239, s[8:9]
	v_mul_f32_e32 v238, v137, v238
	v_cndmask_b32_e64 v238, v238, -v238, s[8:9]
	v_fmac_f32_e32 v238, v4, v136
	v_mov_b32_e32 v4, v238
.LBB0_251:
	s_or_b64 exec, exec, s[54:55]
	v_add_co_u32_e32 v22, vcc, 0x5000, v80
	v_cvt_pk_bf16_f32 v4, v4, s0
	s_nop 0
	v_addc_co_u32_e32 v23, vcc, 0, v81, vcc
	global_store_short v[22:23], v4, off offset:256
	v_mul_f32_e32 v4, v106, v33
	s_and_saveexec_b64 s[54:55], s[12:13]
	s_cbranch_execz .LBB0_253
	v_mov_b32_e32 v238, v4
	v_mov_b32_e32 v239, v4
	s_nop 1
	v_permlane16_swap_b32_e32 v238, v239
	v_cndmask_b32_e64 v238, v238, v239, s[8:9]
	v_mul_f32_e32 v238, v139, v238
	v_cndmask_b32_e64 v238, v238, -v238, s[8:9]
	v_fmac_f32_e32 v238, v4, v138
	v_mov_b32_e32 v4, v238
.LBB0_253:
	s_or_b64 exec, exec, s[54:55]
	v_add_co_u32_e32 v22, vcc, 0x5000, v80
	v_cvt_pk_bf16_f32 v4, v4, s0
	s_nop 0
	v_addc_co_u32_e32 v23, vcc, 0, v81, vcc
	global_store_short v[22:23], v4, off offset:1408
	v_mul_f32_e32 v4, v107, v34
	s_and_saveexec_b64 s[54:55], s[12:13]
	s_cbranch_execz .LBB0_255
	v_mov_b32_e32 v238, v4
	v_mov_b32_e32 v239, v4
	s_nop 1
	v_permlane16_swap_b32_e32 v238, v239
	v_cndmask_b32_e64 v238, v238, v239, s[8:9]
	v_mul_f32_e32 v238, v141, v238
	v_cndmask_b32_e64 v238, v238, -v238, s[8:9]
	v_fmac_f32_e32 v238, v4, v140
	v_mov_b32_e32 v4, v238
.LBB0_255:
	s_or_b64 exec, exec, s[54:55]
	v_add_co_u32_e32 v22, vcc, 0x6000, v80
	v_cvt_pk_bf16_f32 v4, v4, s0
	s_nop 0
	v_addc_co_u32_e32 v23, vcc, 0, v81, vcc
	global_store_short v[22:23], v4, off offset:3072
	v_mul_f32_e32 v4, v108, v35
	s_and_saveexec_b64 s[54:55], s[12:13]
	s_cbranch_execz .LBB0_257
	v_mov_b32_e32 v238, v4
	v_mov_b32_e32 v239, v4
	s_nop 1
	v_permlane16_swap_b32_e32 v238, v239
	v_cndmask_b32_e64 v238, v238, v239, s[8:9]
	v_mul_f32_e32 v238, v143, v238
	v_cndmask_b32_e64 v238, v238, -v238, s[8:9]
	v_fmac_f32_e32 v238, v4, v142
	v_mov_b32_e32 v4, v238
.LBB0_257:
	s_or_b64 exec, exec, s[54:55]
	v_add_co_u32_e32 v22, vcc, 0x7000, v80
	v_cvt_pk_bf16_f32 v4, v4, s0
	s_nop 0
	v_addc_co_u32_e32 v23, vcc, 0, v81, vcc
	global_store_short v[22:23], v4, off offset:128
	v_mul_f32_e32 v4, v109, v36
	s_and_saveexec_b64 s[54:55], s[12:13]
	s_cbranch_execz .LBB0_259
	v_mov_b32_e32 v238, v4
	v_mov_b32_e32 v239, v4
	s_nop 1
	v_permlane16_swap_b32_e32 v238, v239
	v_cndmask_b32_e64 v238, v238, v239, s[8:9]
	v_mul_f32_e32 v238, v145, v238
	v_cndmask_b32_e64 v238, v238, -v238, s[8:9]
	v_fmac_f32_e32 v238, v4, v144
	v_mov_b32_e32 v4, v238
.LBB0_259:
	s_or_b64 exec, exec, s[54:55]
	v_add_co_u32_e32 v22, vcc, 0x7000, v80
	v_cvt_pk_bf16_f32 v4, v4, s0
	s_nop 0
	v_addc_co_u32_e32 v23, vcc, 0, v81, vcc
	global_store_short v[22:23], v4, off offset:1280
	v_mul_f32_e32 v4, v110, v37
	s_and_saveexec_b64 s[54:55], s[12:13]
	s_cbranch_execz .LBB0_261
	v_mov_b32_e32 v238, v4
	v_mov_b32_e32 v239, v4
	s_nop 1
	v_permlane16_swap_b32_e32 v238, v239
	v_cndmask_b32_e64 v238, v238, v239, s[8:9]
	v_mul_f32_e32 v238, v147, v238
	v_cndmask_b32_e64 v238, v238, -v238, s[8:9]
	v_fmac_f32_e32 v238, v4, v146
	v_mov_b32_e32 v4, v238

; DI unsigned pk2(float lo, float hi) { f32x2 v = {lo, hi}; b16x2 r = __builtin_convertvector(v, b16x2); return __builtin_bit_cast(unsigned, r); }
; DI void phase_mla_up(const Params& p, int layer, char* lds) {
;     ...
;       auto epi = [&](const f32x16& acc, const int c0) {
;         if (part == 0) {
;           const bool is_rope = (c0 % 96 == 64);
;           u16* qp = QB + (size_t)rowb * QW + c0 + l32;
;           const f32x2* rp = rt + (size_t)srow * 16 + (l32 & 15);
; #pragma unroll
;           for (int r = 0; r < 16; ++r) {
;             const int ro = (r & 3) + 8 * (r >> 2);
;             float v = acc[r] * rv[r];
;             if (is_rope) {
;               float o = __shfl_xor(v, 16);
;               f32x2 cs = rp[ro * 16];
;               v = (l32 < 16) ? (v * cs[0] - o * cs[1]) : (v * cs[0] + o * cs[1]);
;             }
;             qp[ro * QW] = (u16)(pk2(v, 0.f) & 0xffffu);
;           }
.LBB0_269:
	s_andn2_b64 vcc, exec, s[12:13]
	s_cbranch_vccnz .LBB0_190
	v_mul_hi_i32 v4, v26, s95
	v_lshrrev_b32_e32 v22, 31, v4
	v_lshrrev_b32_e32 v4, 4, v4
	v_add_u32_e32 v4, v4, v22
	v_mul_lo_u32 v4, v4, s61
	v_sub_u32_e32 v4, v26, v4
	v_cmp_eq_u32_e64 s[12:13], 64, v4
	v_mul_f32_e32 v4, v95, v6
	s_and_saveexec_b64 s[54:55], s[12:13]
	s_cbranch_execz .LBB0_272
	v_mov_b32_e32 v238, v4
	v_mov_b32_e32 v239, v4
	s_nop 1
	v_permlane16_swap_b32_e32 v238, v239
	v_cndmask_b32_e64 v238, v238, v239, s[8:9]
	v_mul_f32_e32 v238, v117, v238
	v_cndmask_b32_e64 v238, v238, -v238, s[8:9]
	v_fmac_f32_e32 v238, v4, v116
	v_mov_b32_e32 v4, v238
.LBB0_272:
	s_or_b64 exec, exec, s[54:55]
	v_ashrrev_i32_e32 v79, 31, v78
	v_lshl_add_u64 v[22:23], v[78:79], 1, v[74:75]
	v_cvt_pk_bf16_f32 v4, v4, s0
	global_store_short v[22:23], v4, off offset:64
	v_mul_f32_e32 v4, v96, v7
	s_and_saveexec_b64 s[54:55], s[12:13]
	s_cbranch_execz .LBB0_274
	v_mov_b32_e32 v238, v4
	v_mov_b32_e32 v239, v4
	s_nop 1
	v_permlane16_swap_b32_e32 v238, v239
	v_cndmask_b32_e64 v238, v238, v239, s[8:9]
	v_mul_f32_e32 v238, v119, v238
	v_cndmask_b32_e64 v238, v238, -v238, s[8:9]
	v_fmac_f32_e32 v238, v4, v118
	v_mov_b32_e32 v4, v238
.LBB0_274:
	s_or_b64 exec, exec, s[54:55]
	v_cvt_pk_bf16_f32 v4, v4, s0
	global_store_short v[22:23], v4, off offset:1216
	v_mul_f32_e32 v4, v97, v8
	s_and_saveexec_b64 s[54:55], s[12:13]
	s_cbranch_execz .LBB0_276
	v_mov_b32_e32 v238, v4
	v_mov_b32_e32 v239, v4
	s_nop 1
	v_permlane16_swap_b32_e32 v238, v239
	v_cndmask_b32_e64 v238, v238, v239, s[8:9]
	v_mul_f32_e32 v238, v121, v238
	v_cndmask_b32_e64 v238, v238, -v238, s[8:9]
	v_fmac_f32_e32 v238, v4, v120
	v_mov_b32_e32 v4, v238
.LBB0_276:
	s_or_b64 exec, exec, s[54:55]
	v_cvt_pk_bf16_f32 v4, v4, s0
	global_store_short v[22:23], v4, off offset:2368
	v_mul_f32_e32 v4, v98, v9
	s_and_saveexec_b64 s[54:55], s[12:13]
	s_cbranch_execz .LBB0_278
	v_mov_b32_e32 v238, v4
	v_mov_b32_e32 v239, v4
	s_nop 1
	v_permlane16_swap_b32_e32 v238, v239
	v_cndmask_b32_e64 v238, v238, v239, s[8:9]
	v_mul_f32_e32 v238, v123, v238
	v_cndmask_b32_e64 v238, v238, -v238, s[8:9]
	v_fmac_f32_e32 v238, v4, v122
	v_mov_b32_e32 v4, v238
.LBB0_278:
	s_or_b64 exec, exec, s[54:55]
	v_cvt_pk_bf16_f32 v4, v4, s0
	global_store_short v[22:23], v4, off offset:3520
	v_mul_f32_e32 v4, v99, v10
	s_and_saveexec_b64 s[54:55], s[12:13]
	s_cbranch_execz .LBB0_280
	v_mov_b32_e32 v238, v4
	v_mov_b32_e32 v239, v4
	s_nop 1
	v_permlane16_swap_b32_e32 v238, v239
	v_cndmask_b32_e64 v238, v238, v239, s[8:9]
	v_mul_f32_e32 v238, v125, v238
	v_cndmask_b32_e64 v238, v238, -v238, s[8:9]
	v_fmac_f32_e32 v238, v4, v124
	v_mov_b32_e32 v4, v238
.LBB0_280:
	s_or_b64 exec, exec, s[54:55]
	v_lshl_add_u64 v[6:7], v[22:23], 0, 64
	v_add_co_u32_e32 v8, vcc, 0x2000, v6
	v_cvt_pk_bf16_f32 v4, v4, s0
	s_nop 0
	v_addc_co_u32_e32 v9, vcc, 0, v7, vcc
	global_store_short v[8:9], v4, off offset:1024
	v_mul_f32_e32 v4, v100, v11
	s_and_saveexec_b64 s[54:55], s[12:13]
	s_cbranch_execz .LBB0_282
	v_mov_b32_e32 v238, v4
	v_mov_b32_e32 v239, v4
	s_nop 1
	v_permlane16_swap_b32_e32 v238, v239
	v_cndmask_b32_e64 v238, v238, v239, s[8:9]
	v_mul_f32_e32 v238, v127, v238
	v_cndmask_b32_e64 v238, v238, -v238, s[8:9]
	v_fmac_f32_e32 v238, v4, v126
	v_mov_b32_e32 v4, v238
.LBB0_282:
	s_or_b64 exec, exec, s[54:55]
	v_add_co_u32_e32 v8, vcc, 0x2000, v6
	v_cvt_pk_bf16_f32 v4, v4, s0
	s_nop 0
	v_addc_co_u32_e32 v9, vcc, 0, v7, vcc
	global_store_short v[8:9], v4, off offset:2176
	v_mul_f32_e32 v4, v101, v12
	s_and_saveexec_b64 s[54:55], s[12:13]
	s_cbranch_execz .LBB0_284
	v_mov_b32_e32 v238, v4
	v_mov_b32_e32 v239, v4
	s_nop 1
	v_permlane16_swap_b32_e32 v238, v239
	v_cndmask_b32_e64 v238, v238, v239, s[8:9]
	v_mul_f32_e32 v238, v129, v238
	v_cndmask_b32_e64 v238, v238, -v238, s[8:9]
	v_fmac_f32_e32 v238, v4, v128
	v_mov_b32_e32 v4, v238
.LBB0_284:
	s_or_b64 exec, exec, s[54:55]
	v_add_co_u32_e32 v8, vcc, 0x2000, v6
	v_cvt_pk_bf16_f32 v4, v4, s0
	s_nop 0
	v_addc_co_u32_e32 v9, vcc, 0, v7, vcc
	global_store_short v[8:9], v4, off offset:3328
	v_mul_f32_e32 v4, v102, v13
	s_and_saveexec_b64 s[54:55], s[12:13]
	s_cbranch_execz .LBB0_286
	v_mov_b32_e32 v238, v4
	v_mov_b32_e32 v239, v4
	s_nop 1
	v_permlane16_swap_b32_e32 v238, v239
	v_cndmask_b32_e64 v238, v238, v239, s[8:9]
	v_mul_f32_e32 v238, v131, v238
	v_cndmask_b32_e64 v238, v238, -v238, s[8:9]
	v_fmac_f32_e32 v238, v4, v130
	v_mov_b32_e32 v4, v238
; DI unsigned pk2(float lo, float hi) { f32x2 v = {lo, hi}; b16x2 r = __builtin_convertvector(v, b16x2); return __builtin_bit_cast(unsigned, r); }
; DI void phase_mla_up(const Params& p, int layer, char* lds) {
;     ...
;           for (int r = 0; r < 16; ++r) {
;             const int ro = (r & 3) + 8 * (r >> 2);
;             float v = acc[r] * rv[r];
;             if (is_rope) {
;               float o = __shfl_xor(v, 16);
;               f32x2 cs = rp[ro * 16];
;               v = (l32 < 16) ? (v * cs[0] - o * cs[1]) : (v * cs[0] + o * cs[1]);
;             }
;             qp[ro * QW] = (u16)(pk2(v, 0.f) & 0xffffu);
;           }
.LBB0_286:
	s_or_b64 exec, exec, s[54:55]
	v_add_co_u32_e32 v8, vcc, 0x3000, v6
	v_cvt_pk_bf16_f32 v4, v4, s0
	s_nop 0
	v_addc_co_u32_e32 v9, vcc, 0, v7, vcc
	global_store_short v[8:9], v4, off offset:384
	v_mul_f32_e32 v4, v103, v14
	s_and_saveexec_b64 s[54:55], s[12:13]
	s_cbranch_execz .LBB0_288
	v_mov_b32_e32 v238, v4
	v_mov_b32_e32 v239, v4
	s_nop 1
	v_permlane16_swap_b32_e32 v238, v239
	v_cndmask_b32_e64 v238, v238, v239, s[8:9]
	v_mul_f32_e32 v238, v133, v238
	v_cndmask_b32_e64 v238, v238, -v238, s[8:9]
	v_fmac_f32_e32 v238, v4, v132
	v_mov_b32_e32 v4, v238
.LBB0_288:
	s_or_b64 exec, exec, s[54:55]
	v_add_co_u32_e32 v8, vcc, 0x4000, v6
	v_cvt_pk_bf16_f32 v4, v4, s0
	s_nop 0
	v_addc_co_u32_e32 v9, vcc, 0, v7, vcc
	global_store_short v[8:9], v4, off offset:2048
	v_mul_f32_e32 v4, v104, v15
	s_and_saveexec_b64 s[54:55], s[12:13]
	s_cbranch_execz .LBB0_290
	v_mov_b32_e32 v238, v4
	v_mov_b32_e32 v239, v4
	s_nop 1
	v_permlane16_swap_b32_e32 v238, v239
	v_cndmask_b32_e64 v238, v238, v239, s[8:9]
	v_mul_f32_e32 v238, v135, v238
	v_cndmask_b32_e64 v238, v238, -v238, s[8:9]
	v_fmac_f32_e32 v238, v4, v134
	v_mov_b32_e32 v4, v238
.LBB0_290:
	s_or_b64 exec, exec, s[54:55]
	v_add_co_u32_e32 v8, vcc, 0x4000, v6
	v_cvt_pk_bf16_f32 v4, v4, s0
	s_nop 0
	v_addc_co_u32_e32 v9, vcc, 0, v7, vcc
	global_store_short v[8:9], v4, off offset:3200
	v_mul_f32_e32 v4, v105, v16
	s_and_saveexec_b64 s[54:55], s[12:13]
	s_cbranch_execz .LBB0_292
	v_mov_b32_e32 v238, v4
	v_mov_b32_e32 v239, v4
	s_nop 1
	v_permlane16_swap_b32_e32 v238, v239
	v_cndmask_b32_e64 v238, v238, v239, s[8:9]
	v_mul_f32_e32 v238, v137, v238
	v_cndmask_b32_e64 v238, v238, -v238, s[8:9]
	v_fmac_f32_e32 v238, v4, v136
	v_mov_b32_e32 v4, v238
.LBB0_292:
	s_or_b64 exec, exec, s[54:55]
	v_add_co_u32_e32 v8, vcc, 0x5000, v6
	v_cvt_pk_bf16_f32 v4, v4, s0
	s_nop 0
	v_addc_co_u32_e32 v9, vcc, 0, v7, vcc
	global_store_short v[8:9], v4, off offset:256
	v_mul_f32_e32 v4, v106, v17
	s_and_saveexec_b64 s[54:55], s[12:13]
	s_cbranch_execz .LBB0_294
	v_mov_b32_e32 v238, v4
	v_mov_b32_e32 v239, v4
	s_nop 1
	v_permlane16_swap_b32_e32 v238, v239
	v_cndmask_b32_e64 v238, v238, v239, s[8:9]
	v_mul_f32_e32 v238, v139, v238
	v_cndmask_b32_e64 v238, v238, -v238, s[8:9]
	v_fmac_f32_e32 v238, v4, v138
	v_mov_b32_e32 v4, v238
.LBB0_294:
	s_or_b64 exec, exec, s[54:55]
	v_add_co_u32_e32 v8, vcc, 0x5000, v6
	v_cvt_pk_bf16_f32 v4, v4, s0
	s_nop 0
	v_addc_co_u32_e32 v9, vcc, 0, v7, vcc
	global_store_short v[8:9], v4, off offset:1408
	v_mul_f32_e32 v4, v107, v18
	s_and_saveexec_b64 s[54:55], s[12:13]
	s_cbranch_execz .LBB0_296
	v_mov_b32_e32 v238, v4
	v_mov_b32_e32 v239, v4
	s_nop 1
	v_permlane16_swap_b32_e32 v238, v239
	v_cndmask_b32_e64 v238, v238, v239, s[8:9]
	v_mul_f32_e32 v238, v141, v238
	v_cndmask_b32_e64 v238, v238, -v238, s[8:9]
	v_fmac_f32_e32 v238, v4, v140
	v_mov_b32_e32 v4, v238
.LBB0_296:
	s_or_b64 exec, exec, s[54:55]
	v_add_co_u32_e32 v8, vcc, 0x6000, v6
	v_cvt_pk_bf16_f32 v4, v4, s0
	s_nop 0
	v_addc_co_u32_e32 v9, vcc, 0, v7, vcc
	global_store_short v[8:9], v4, off offset:3072
	v_mul_f32_e32 v4, v108, v19
	s_and_saveexec_b64 s[54:55], s[12:13]
	s_cbranch_execz .LBB0_298
	v_mov_b32_e32 v238, v4
	v_mov_b32_e32 v239, v4
	s_nop 1
	v_permlane16_swap_b32_e32 v238, v239
	v_cndmask_b32_e64 v238, v238, v239, s[8:9]
	v_mul_f32_e32 v238, v143, v238
	v_cndmask_b32_e64 v238, v238, -v238, s[8:9]
	v_fmac_f32_e32 v238, v4, v142
	v_mov_b32_e32 v4, v238
.LBB0_298:
	s_or_b64 exec, exec, s[54:55]
	v_add_co_u32_e32 v8, vcc, 0x7000, v6
	v_cvt_pk_bf16_f32 v4, v4, s0
	s_nop 0
	v_addc_co_u32_e32 v9, vcc, 0, v7, vcc
	global_store_short v[8:9], v4, off offset:128
	v_mul_f32_e32 v4, v109, v20
	s_and_saveexec_b64 s[54:55], s[12:13]
	s_cbranch_execz .LBB0_300
	v_mov_b32_e32 v238, v4
	v_mov_b32_e32 v239, v4
	s_nop 1
	v_permlane16_swap_b32_e32 v238, v239
	v_cndmask_b32_e64 v238, v238, v239, s[8:9]
	v_mul_f32_e32 v238, v145, v238
	v_cndmask_b32_e64 v238, v238, -v238, s[8:9]
	v_fmac_f32_e32 v238, v4, v144
	v_mov_b32_e32 v4, v238
.LBB0_300:
	s_or_b64 exec, exec, s[54:55]
	v_add_co_u32_e32 v8, vcc, 0x7000, v6
	v_cvt_pk_bf16_f32 v4, v4, s0
	s_nop 0
	v_addc_co_u32_e32 v9, vcc, 0, v7, vcc
	global_store_short v[8:9], v4, off offset:1280
	v_mul_f32_e32 v4, v110, v21
	s_and_saveexec_b64 s[54:55], s[12:13]
	s_cbranch_execz .LBB0_189
	v_mov_b32_e32 v238, v4
	v_mov_b32_e32 v239, v4
	s_nop 1
	v_permlane16_swap_b32_e32 v238, v239
	v_cndmask_b32_e64 v238, v238, v239, s[8:9]
	v_mul_f32_e32 v238, v147, v238
	v_cndmask_b32_e64 v238, v238, -v238, s[8:9]
	v_fmac_f32_e32 v238, v4, v146
	v_mov_b32_e32 v4, v238
	s_branch .LBB0_189
